# RWKV-7 state scan: first chunk step's eight decay-vector LDS reads issued together ahead of the state conversions (one wait instead of three); hazard pads in the RWKV record prefetch block
# speedup vs baseline: 1.0116x; 1.0015x over previous
.LBB0_433:
	s_mul_i32 s1, s0, 37
	s_bfe_u32 s2, s1, 0x80008
	s_lshr_b32 s1, s1, 8
	s_sub_i32 s1, s0, s1
	s_bfe_u32 s1, s1, 0x70001
	s_add_i32 s1, s1, s2
	s_bfe_u32 s1, s1, 0x60002
	s_mul_i32 s1, s1, 7
	s_sub_i32 s1, s0, s1
	s_and_b32 s1, s1, 0xff
	s_mulk_i32 s1, 0x4800
	v_add_u32_e32 v136, s1, v151
	ds_read_b128 v[32:35], v136 offset:17792
	ds_read_b128 v[36:39], v136 offset:17824
	ds_read_b128 v[40:43], v136 offset:17856
	ds_read_b128 v[44:47], v136 offset:17888
	ds_read_b128 v[128:131], v136 offset:17920
	ds_read_b128 v[132:135], v136 offset:17952
	ds_read_b128 v[220:223], v136 offset:17984
	ds_read_b128 v[224:227], v136 offset:18016
	v_cvt_pk_bf16_f32 v112, v16, v17
	v_cvt_pk_bf16_f32 v113, v18, v19
	v_cvt_pk_bf16_f32 v114, v20, v21
	v_cvt_pk_bf16_f32 v115, v22, v23
	v_cvt_pk_bf16_f32 v116, v24, v25
	v_cvt_pk_bf16_f32 v117, v26, v27
	v_cvt_pk_bf16_f32 v118, v28, v29
	v_cvt_pk_bf16_f32 v119, v30, v31
	v_cvt_pk_bf16_f32 v120, v0, v1
	v_cvt_pk_bf16_f32 v121, v2, v3
	v_cvt_pk_bf16_f32 v122, v4, v5
	v_cvt_pk_bf16_f32 v123, v6, v7
	v_cvt_pk_bf16_f32 v124, v8, v9
	v_cvt_pk_bf16_f32 v125, v10, v11
	v_cvt_pk_bf16_f32 v126, v12, v13
	v_cvt_pk_bf16_f32 v127, v14, v15
	s_waitcnt lgkmcnt(0)
	v_pk_mul_f32 v[16:17], v[16:17], v[32:33]
	v_pk_mul_f32 v[18:19], v[18:19], v[34:35]
	v_pk_mul_f32 v[20:21], v[20:21], v[36:37]
	v_pk_mul_f32 v[22:23], v[22:23], v[38:39]
	v_pk_mul_f32 v[24:25], v[24:25], v[40:41]
	v_pk_mul_f32 v[26:27], v[26:27], v[42:43]
	v_pk_mul_f32 v[28:29], v[28:29], v[44:45]
	v_pk_mul_f32 v[30:31], v[30:31], v[46:47]
	v_mfma_f32_32x32x16_bf16 v[32:47], v[48:51], v[112:115], 0
	v_mul_f32_e64 v0, v0, v128
	v_mul_f32_e64 v1, v1, v129
	v_mul_f32_e64 v2, v2, v130
	v_mul_f32_e64 v3, v3, v131
	v_mul_f32_e64 v4, v4, v132
	v_mul_f32_e64 v5, v5, v133
	v_pk_mul_f32 v[6:7], v[6:7], v[134:135]
	s_or_b32 s1, s0, 1
	v_mfma_f32_32x32x16_bf16 v[16:31], v[72:75], v[112:115], v[16:31]
	s_and_b32 s2, s1, 0xff
	v_mul_f32_e64 v8, v8, v220
	v_mul_f32_e64 v9, v9, v221
	v_mul_f32_e64 v10, v10, v222
	v_mul_f32_e64 v11, v11, v223
	v_pk_mul_f32 v[12:13], v[12:13], v[224:225]
	v_pk_mul_f32 v[14:15], v[14:15], v[226:227]
	s_mul_i32 s2, s2, 37
	s_lshr_b32 s2, s2, 8
	v_mfma_f32_32x32x16_bf16 v[32:47], v[52:55], v[116:119], v[32:47]
	s_sub_i32 s3, s1, s2
	s_bfe_u32 s3, s3, 0x70001
	s_add_i32 s3, s3, s2
	s_lshr_b32 s2, s3, 2
	s_mul_i32 s2, s2, 7
	s_sub_i32 s1, s1, s2
	s_and_b32 s1, s1, 0xff
	v_mfma_f32_32x32x16_bf16 v[0:15], v[88:91], v[112:115], v[0:15]
	s_mulk_i32 s1, 0x4800
	s_add_i32 s1, s1, 0
	v_add_u32_e32 v192, s1, v144
	v_add_u32_e32 v180, v192, v156
	s_cmpk_gt_u32 s0, 0x7d
	s_cselect_b64 s[2:3], -1, 0
	v_mfma_f32_32x32x16_bf16 v[16:31], v[76:79], v[116:119], v[16:31]
	s_and_b64 vcc, exec, s[2:3]
	v_mfma_f32_32x32x16_bf16 v[32:47], v[56:59], v[120:123], v[32:47]
	v_mfma_f32_32x32x16_bf16 v[0:15], v[92:95], v[116:119], v[0:15]
	v_mfma_f32_32x32x16_bf16 v[16:31], v[80:83], v[120:123], v[16:31]
	v_mfma_f32_32x32x16_bf16 v[32:47], v[60:63], v[124:127], v[32:47]
	v_mfma_f32_32x32x16_bf16 v[0:15], v[96:99], v[120:123], v[0:15]
	v_mfma_f32_32x32x16_bf16 v[16:31], v[84:87], v[124:127], v[16:31]
	v_mfma_f32_32x32x16_bf16 v[32:47], v[68:71], v[64:67], v[32:47]
	v_mfma_f32_32x32x16_bf16 v[0:15], v[100:103], v[124:127], v[0:15]
	s_nop 10
	v_add_u32_e32 v45, s1, v153
	v_add_u32_e32 v46, v45, v152
	v_add_u32_e32 v160, v45, v155
	v_add_u32_e32 v44, v192, v150
	ds_read2_b64 v[40:43], v46 offset1:2
	ds_read2_b64 v[116:119], v46 offset0:4 offset1:6
	ds_read2_b64 v[120:123], v46 offset0:8 offset1:10
	ds_read2_b64 v[124:127], v46 offset0:12 offset1:14
	v_add_u32_e32 v46, v192, v154
	v_add_u32_e32 v132, 0x800, v160
	v_mfma_f32_32x32x16_bf16 v[16:31], v[104:107], v[64:67], v[16:31]
	v_add_u32_e32 v172, 0x1800, v160
	ds_read_b128 v[112:115], v44 offset:14720
	ds_read_b128 v[128:131], v46 offset:2176
	ds_read2_b64 v[44:47], v132 offset0:112 offset1:114
	ds_read2_b64 v[140:143], v132 offset0:116 offset1:118
	ds_read2_b64 v[136:139], v132 offset0:120 offset1:122
	ds_read2_b64 v[132:135], v132 offset0:124 offset1:126
	ds_read2_b64 v[160:163], v172 offset0:144 offset1:146
	ds_read2_b64 v[164:167], v172 offset0:148 offset1:150
	ds_read2_b64 v[168:171], v172 offset0:152 offset1:154
	ds_read2_b64 v[172:175], v172 offset0:156 offset1:158
	ds_read_b128 v[176:179], v180 offset:11648
	ds_read_b128 v[180:183], v180 offset:13184
	ds_read_b128 v[220:223], v192 offset:17888
	ds_read_b128 v[224:227], v192 offset:17856
	ds_read_b128 v[228:231], v192 offset:17824
	ds_read_b128 v[232:235], v192 offset:17792
	ds_read_b128 v[236:239], v192 offset:18016
	ds_read_b128 v[240:243], v192 offset:17984
	ds_read_b128 v[244:247], v192 offset:17952
	ds_write2st64_b32 v158, v32, v33 offset1:1
	ds_write2st64_b32 v158, v34, v35 offset0:2 offset1:3
	ds_write2st64_b32 v158, v36, v37 offset0:8 offset1:9
	ds_write2st64_b32 v158, v38, v39 offset0:10 offset1:11
	s_waitcnt lgkmcnt(0)
	s_barrier
	ds_read_b128 v[36:39], v192 offset:17920
	v_cvt_pk_bf16_f32 v32, v16, v17
	v_mfma_f32_32x32x16_bf16 v[0:15], v[108:111], v[64:67], v[0:15]
	v_cvt_pk_bf16_f32 v33, v18, v19
	v_cvt_pk_bf16_f32 v34, v20, v21
	v_cvt_pk_bf16_f32 v35, v22, v23
	v_cvt_pk_bf16_f32 v184, v24, v25
	v_cvt_pk_bf16_f32 v185, v26, v27
	v_cvt_pk_bf16_f32 v186, v28, v29
	v_cvt_pk_bf16_f32 v187, v30, v31
	v_cvt_pk_bf16_f32 v188, v0, v1
	v_cvt_pk_bf16_f32 v189, v2, v3
	v_cvt_pk_bf16_f32 v190, v4, v5
	v_cvt_pk_bf16_f32 v191, v6, v7
	v_cvt_pk_bf16_f32 v216, v8, v9
	v_cvt_pk_bf16_f32 v217, v10, v11
	v_cvt_pk_bf16_f32 v218, v12, v13
	v_cvt_pk_bf16_f32 v219, v14, v15
	v_pk_mul_f32 v[28:29], v[28:29], v[220:221]
	v_pk_mul_f32 v[30:31], v[30:31], v[222:223]
	v_pk_mul_f32 v[24:25], v[24:25], v[224:225]
	v_pk_mul_f32 v[26:27], v[26:27], v[226:227]
	v_pk_mul_f32 v[20:21], v[20:21], v[228:229]
	v_pk_mul_f32 v[22:23], v[22:23], v[230:231]
	v_pk_mul_f32 v[18:19], v[18:19], v[234:235]
	v_pk_mul_f32 v[16:17], v[16:17], v[232:233]
	v_pk_mul_f32 v[12:13], v[12:13], v[236:237]
	v_pk_mul_f32 v[14:15], v[14:15], v[238:239]
	v_mfma_f32_32x32x16_bf16 v[16:31], v[44:47], v[32:35], v[16:31]
	v_mul_f32_e64 v8, v8, v240
	v_mul_f32_e64 v9, v9, v241
	v_mul_f32_e64 v10, v10, v242
	v_mul_f32_e64 v11, v11, v243
	v_pk_mul_f32 v[4:5], v[4:5], v[244:245]
	v_pk_mul_f32 v[6:7], v[6:7], v[246:247]
	v_mfma_f32_32x32x16_bf16 v[16:31], v[140:143], v[184:187], v[16:31]
	s_waitcnt lgkmcnt(0)
	v_mul_f32_e64 v2, v2, v38
	v_mul_f32_e64 v3, v3, v39
	v_mul_f32_e64 v0, v0, v36
	v_mul_f32_e64 v1, v1, v37
	s_nop 1
	v_mfma_f32_32x32x16_bf16 v[0:15], v[160:163], v[32:35], v[0:15]
	v_mfma_f32_32x32x16_bf16 v[32:47], v[40:43], v[32:35], 0
	v_mfma_f32_32x32x16_bf16 v[32:47], v[116:119], v[184:187], v[32:47]
	v_mfma_f32_32x32x16_bf16 v[0:15], v[164:167], v[184:187], v[0:15]
	v_mfma_f32_32x32x16_bf16 v[32:47], v[120:123], v[188:191], v[32:47]
	v_mfma_f32_32x32x16_bf16 v[16:31], v[136:139], v[188:191], v[16:31]
	v_mfma_f32_32x32x16_bf16 v[0:15], v[168:171], v[188:191], v[0:15]
	v_mfma_f32_32x32x16_bf16 v[32:47], v[124:127], v[216:219], v[32:47]
	v_mfma_f32_32x32x16_bf16 v[16:31], v[132:135], v[216:219], v[16:31]
	v_mfma_f32_32x32x16_bf16 v[0:15], v[172:175], v[216:219], v[0:15]
	v_mfma_f32_32x32x16_bf16 v[32:47], v[128:131], v[112:115], v[32:47]
	v_mfma_f32_32x32x16_bf16 v[16:31], v[176:179], v[112:115], v[16:31]
	v_mfma_f32_32x32x16_bf16 v[0:15], v[180:183], v[112:115], v[0:15]
	s_cbranch_vccnz .LBB0_432
	s_add_i32 s1, s0, 2
	s_and_b32 s4, s1, 0xff
	s_mul_i32 s4, s4, 37
	s_lshr_b32 s5, s4, 8
	s_sub_i32 s5, s1, s5
	s_bfe_u32 s5, s5, 0x70001
	s_bfe_u32 s4, s4, 0x80008
	s_add_i32 s5, s5, s4
	s_bfe_u32 s4, s5, 0x60002
	s_mul_i32 s4, s4, 7
	s_sub_i32 s1, s1, s4
	s_and_b32 s1, s1, 0xff
	s_mulk_i32 s1, 0x4800
	s_add_i32 s1, s1, 0
	v_add_u32_e32 v40, s1, v144
	v_add_u32_e32 v42, s1, v153
	v_add_u32_e32 v41, v40, v150
	v_add_u32_e32 v43, v42, v152
	ds_read2_b64 v[48:51], v43 offset1:2
	ds_read2_b64 v[52:55], v43 offset0:4 offset1:6
	ds_read2_b64 v[56:59], v43 offset0:8 offset1:10
	ds_read2_b64 v[60:63], v43 offset0:12 offset1:14
	v_add_u32_e32 v43, v40, v154
	ds_read_b128 v[64:67], v41 offset:14720
	ds_read_b128 v[68:71], v43 offset:2176
	v_add_u32_e32 v41, v42, v155
	v_add_u32_e32 v42, 0x800, v41
	v_add_u32_e32 v41, 0x1800, v41
	ds_read2_b64 v[72:75], v42 offset0:112 offset1:114
	ds_read2_b64 v[76:79], v42 offset0:116 offset1:118
	ds_read2_b64 v[80:83], v42 offset0:120 offset1:122
	ds_read2_b64 v[84:87], v42 offset0:124 offset1:126
	v_add_u32_e32 v40, v40, v156
	ds_read2_b64 v[88:91], v41 offset0:144 offset1:146
	ds_read2_b64 v[92:95], v41 offset0:148 offset1:150
	ds_read2_b64 v[96:99], v41 offset0:152 offset1:154
	ds_read2_b64 v[100:103], v41 offset0:156 offset1:158
	ds_read_b128 v[104:107], v40 offset:11648
	ds_read_b128 v[108:111], v40 offset:13184
	s_branch .LBB0_432
